# attention pass 2: 3-buffer K ring, first half of next tile K fragments prefetched during PV, lsum adds as in-place packed tree
# baseline (speedup 1.0000x reference)
.LBB0_130:
	s_or_b64 exec, exec, s[4:5]
	v_ashrrev_i32_e32 v42, 2, v40
	v_and_b32_e32 v36, 3, v40
	v_lshrrev_b32_e32 v26, 1, v40
	v_bfe_u32 v27, v40, 1, 3
	v_mad_i64_i32 v[34:35], s[4:5], s34, v42, 0
	v_bitop3_b32 v26, v105, v26, 7 bitop3:0x78
	v_bitop3_b32 v27, v105, v27, 4 bitop3:0x36
	v_lshl_add_u64 v[28:29], v[24:25], 0, v[132:133]
	v_lshl_add_u64 v[34:35], v[34:35], 1, s[16:17]
	v_lshlrev_b32_e32 v132, 5, v36
	v_lshlrev_b32_e32 v121, 4, v26
	v_lshlrev_b32_e32 v119, 4, v27
	global_load_dwordx4 v[24:27], v[28:29], off offset:16
	s_nop 0
	global_load_dwordx4 v[28:31], v[28:29], off
	v_lshl_add_u64 v[38:39], v[34:35], 0, v[132:133]
	v_lshrrev_b32_e32 v17, 3, v40
	v_bfe_u32 v19, v40, 3, 3
	v_lshlrev_b32_e32 v23, 1, v36
	v_lshlrev_b32_e32 v120, 7, v41
	global_load_dwordx4 v[34:37], v[38:39], off offset:16
	s_nop 0
	global_load_dwordx4 v[38:41], v[38:39], off
	v_lshl_add_u64 v[92:93], v[32:33], 0, s[76:77]
	global_load_dwordx4 v[88:91], v[92:93], off
	global_load_dwordx4 v[92:95], v[92:93], off offset:16
	v_lshlrev_b32_e32 v22, 7, v42
	v_bitop3_b32 v17, v23, v17, 7 bitop3:0x78
	v_lshl_or_b32 v122, v17, 4, v22
	v_bitop3_b32 v17, v23, v19, 1 bitop3:0x36
	v_lshl_or_b32 v123, v17, 4, v22
	ds_bpermute_b32 v17, v114, v16
	ds_bpermute_b32 v22, v114, v21
	v_max_f32_e32 v16, v16, v16
	v_max_f32_e32 v21, v21, v21
	v_add3_u32 v43, s91, v116, v117
	s_waitcnt lgkmcnt(1)
	v_max_f32_e32 v17, v17, v17
	s_waitcnt lgkmcnt(0)
	v_max_f32_e32 v22, v22, v22
	v_max_f32_e32 v16, v16, v17
	v_max_f32_e32 v21, v21, v22
	ds_bpermute_b32 v17, v115, v16
	ds_bpermute_b32 v22, v115, v21
	s_add_i32 s23, s23, -1
	s_waitcnt vmcnt(2)
	ds_write_b128 v43, v[28:31]
	ds_write_b128 v43, v[24:27] offset:16
	v_add_u32_e32 v24, 0, v122
	s_waitcnt lgkmcnt(3)
	v_max_f32_e32 v17, v17, v17
	s_waitcnt lgkmcnt(2)
	v_max_f32_e32 v22, v22, v22
	v_max_f32_e32 v16, v16, v17
	v_max_f32_e32 v21, v21, v22
	s_waitcnt vmcnt(0)
	ds_write_b128 v24, v[38:41] offset:34816
	v_add_u32_e32 v24, 0, v123
	ds_write_b128 v24, v[34:37] offset:34816
	s_mov_b32 s5, 0x10800
	v_add3_u32 v96, s5, v116, v117
	ds_write_b128 v96, v[88:91]
	ds_write_b128 v96, v[92:95] offset:16
	v_lshlrev_b32_e32 v24, 1, v42
	v_mad_i64_i32 v[24:25], s[4:5], v24, s34, v[132:133]
	v_cndmask_b32_e32 v16, v18, v16, vcc
	v_cndmask_b32_e32 v20, v20, v21, vcc
	v_lshl_add_u64 v[24:25], s[16:17], 0, v[24:25]
	s_mov_b64 s[4:5], 0x90
	v_xor_b32_e32 v16, 0x80000000, v16
	v_xor_b32_e32 v20, 0x80000000, v20
	v_lshl_add_u64 v[106:107], v[24:25], 0, s[4:5]
	s_mov_b64 s[4:5], 0x8010
	v_mov_b32_e32 v24, 0
	v_mov_b32_e32 v17, v16
	v_mov_b32_e32 v18, v16
	v_mov_b32_e32 v19, v16
	v_mov_b32_e32 v21, v20
	v_mov_b32_e32 v22, v20
	v_mov_b32_e32 v23, v20
	v_lshl_add_u64 v[108:109], v[32:33], 0, s[4:5]
	s_mov_b32 s4, 0
	v_mov_b32_e32 v25, v24
	v_mov_b32_e32 v26, v24
	v_mov_b32_e32 v27, v24
	v_mov_b32_e32 v28, v24
	v_mov_b32_e32 v29, v24
	v_mov_b32_e32 v30, v24
	v_mov_b32_e32 v31, v24
	v_mov_b32_e32 v32, v24
	v_mov_b32_e32 v33, v24
	v_mov_b32_e32 v34, v24
	v_mov_b32_e32 v35, v24
	v_mov_b32_e32 v36, v24
	v_mov_b32_e32 v37, v24
	v_mov_b32_e32 v38, v24
	v_mov_b32_e32 v39, v24
	v_mov_b32_e32 v56, v24
	v_mov_b32_e32 v57, v24
	v_mov_b32_e32 v58, v24
	v_mov_b32_e32 v59, v24
	v_mov_b32_e32 v60, v24
	v_mov_b32_e32 v61, v24
	v_mov_b32_e32 v62, v24
	v_mov_b32_e32 v63, v24
	v_mov_b32_e32 v68, v24
	v_mov_b32_e32 v69, v24
	v_mov_b32_e32 v70, v24
	v_mov_b32_e32 v71, v24
	v_mov_b32_e32 v72, v24
	v_mov_b32_e32 v73, v24
	v_mov_b32_e32 v74, v24
	v_mov_b32_e32 v75, v24
	v_mov_b32_e32 v40, v24
	v_mov_b32_e32 v41, v24
	v_mov_b32_e32 v42, v24
	v_mov_b32_e32 v43, v24
	v_mov_b32_e32 v44, v24
	v_mov_b32_e32 v45, v24
	v_mov_b32_e32 v46, v24
	v_mov_b32_e32 v47, v24
	v_mov_b32_e32 v48, v24
	v_mov_b32_e32 v49, v24
	v_mov_b32_e32 v50, v24
	v_mov_b32_e32 v51, v24
	v_mov_b32_e32 v52, v24
	v_mov_b32_e32 v53, v24
	v_mov_b32_e32 v54, v24
	v_mov_b32_e32 v55, v24
	v_mov_b32_e32 v64, v24
	v_mov_b32_e32 v65, v24
	v_mov_b32_e32 v66, v24
	v_mov_b32_e32 v67, v24
	v_mov_b32_e32 v76, v24
	v_mov_b32_e32 v77, v24
	v_mov_b32_e32 v78, v24
	v_mov_b32_e32 v79, v24
	v_mov_b32_e32 v80, v24
	v_mov_b32_e32 v81, v24
	v_mov_b32_e32 v82, v24
	v_mov_b32_e32 v83, v24
	v_mov_b32_e32 v84, v24
	v_mov_b32_e32 v85, v24
	v_mov_b32_e32 v86, v24
	v_mov_b32_e32 v87, v24
	v_mov_b32_e32 v110, v24
	v_mov_b32_e32 v111, v24
	s_mov_b32 s16, 0x4400
	s_mov_b32 s17, 0x10800
	s_mov_b32 s18, 0
	s_waitcnt lgkmcnt(0)
	s_barrier
	v_add_u32_e32 v132, s16, v118
	ds_read_b128 v[240:243], v132
	ds_read_b128 v[128:131], v132 offset:64
	ds_read_b128 v[244:247], v132 offset:128
	ds_read_b128 v[248:251], v132 offset:192
	ds_read_b128 v[200:203], v132 offset:4352
	ds_read_b128 v[162:165], v132 offset:4416
	ds_read_b128 v[166:169], v132 offset:4480
	ds_read_b128 v[170:173], v132 offset:4544
	s_waitcnt lgkmcnt(0)
.LBB0_131:
	global_load_dwordx4 v[88:91], v[108:109], off
	global_load_dwordx4 v[92:95], v[108:109], off offset:-16
	global_load_dwordx4 v[96:99], v[106:107], off
	global_load_dwordx4 v[100:103], v[106:107], off offset:-16
	s_add_i32 s5, s4, 1
	s_bitcmp1_b32 s4, 0
	v_add_u32_e32 v132, s16, v118
	ds_read_b128 v[174:177], v132 offset:8704
	ds_read_b128 v[178:181], v132 offset:8768
	ds_read_b128 v[182:185], v132 offset:8832
	ds_read_b128 v[186:189], v132 offset:8896
	ds_read_b128 v[216:219], v132 offset:13056
	ds_read_b128 v[220:223], v132 offset:13120
	ds_read_b128 v[224:227], v132 offset:13184
	ds_read_b128 v[228:231], v132 offset:13248
	s_cselect_b32 s4, s57, s70
	v_mfma_f32_16x16x32_bf16 v[124:127], v[240:243], v[12:15], v[16:19]
	v_mfma_f32_16x16x32_bf16 v[124:127], v[128:131], v[0:3], v[124:127]
	v_mfma_f32_16x16x32_bf16 v[128:131], v[244:247], v[4:7], v[20:23]
	v_mfma_f32_16x16x32_bf16 v[128:131], v[248:251], v[8:11], v[128:131]
	v_mfma_f32_16x16x32_bf16 v[150:153], v[200:203], v[12:15], v[16:19]
	v_mfma_f32_16x16x32_bf16 v[154:157], v[166:169], v[4:7], v[20:23]
	v_mfma_f32_16x16x32_bf16 v[150:153], v[162:165], v[0:3], v[150:153]
	v_mfma_f32_16x16x32_bf16 v[154:157], v[170:173], v[8:11], v[154:157]
	s_waitcnt lgkmcnt(7)
	v_mfma_f32_16x16x32_bf16 v[158:161], v[174:177], v[12:15], v[16:19]
	s_waitcnt lgkmcnt(5)
	v_mfma_f32_16x16x32_bf16 v[162:165], v[182:185], v[4:7], v[20:23]
	s_waitcnt lgkmcnt(3)
	v_mfma_f32_16x16x32_bf16 v[166:169], v[216:219], v[12:15], v[16:19]
	s_waitcnt lgkmcnt(1)
	v_mfma_f32_16x16x32_bf16 v[170:173], v[224:227], v[4:7], v[20:23]
	v_mfma_f32_16x16x32_bf16 v[158:161], v[178:181], v[0:3], v[158:161]
	v_mfma_f32_16x16x32_bf16 v[162:165], v[186:189], v[8:11], v[162:165]
	v_mfma_f32_16x16x32_bf16 v[166:169], v[220:223], v[0:3], v[166:169]
	s_waitcnt lgkmcnt(0)
	v_mfma_f32_16x16x32_bf16 v[170:173], v[228:231], v[8:11], v[170:173]
	v_add_u32_e32 v132, s4, v120
	v_add_u32_e32 v190, v132, v121
	ds_read_b128 v[174:177], v190
	ds_read_b128 v[178:181], v190 offset:2048
	ds_read_b128 v[182:185], v190 offset:4096
	ds_read_b128 v[186:189], v190 offset:6144
	ds_read_b128 v[216:219], v190 offset:8192
	ds_read_b128 v[220:223], v190 offset:10240
	ds_read_b128 v[224:227], v190 offset:12288
	ds_read_b128 v[228:231], v190 offset:14336
	v_exp_f32_e32 v191, v124
	v_exp_f32_e32 v190, v128
	v_exp_f32_e32 v241, v125
	v_exp_f32_e32 v240, v129
	v_exp_f32_e32 v243, v126
	v_exp_f32_e32 v242, v130
	v_exp_f32_e32 v245, v127
	v_exp_f32_e32 v244, v131
	v_exp_f32_e32 v247, v150
	v_exp_f32_e32 v246, v154
	v_exp_f32_e32 v249, v151
	v_exp_f32_e32 v248, v155
	v_exp_f32_e32 v251, v152
	v_exp_f32_e32 v250, v156
	v_exp_f32_e32 v253, v153
	v_exp_f32_e32 v252, v157
	v_cvt_pk_bf16_f32 v124, v191, v241
	v_cvt_pk_bf16_f32 v125, v243, v245
	v_cvt_pk_bf16_f32 v126, v247, v249
	v_cvt_pk_bf16_f32 v127, v251, v253
	v_cvt_pk_bf16_f32 v128, v190, v240
	v_cvt_pk_bf16_f32 v129, v242, v244
	v_cvt_pk_bf16_f32 v130, v246, v248
	v_cvt_pk_bf16_f32 v131, v250, v252
	v_add_u32_e32 v132, v132, v119
	s_waitcnt lgkmcnt(7)
	v_mfma_f32_16x16x32_bf16 v[72:75], v[174:177], v[124:127], v[72:75]
	ds_read_b128 v[150:153], v132
	ds_read_b128 v[154:157], v132 offset:2048
	v_exp_f32_e32 v201, v158
	v_exp_f32_e32 v200, v162
	v_mfma_f32_16x16x32_bf16 v[84:87], v[174:177], v[128:131], v[84:87]
	v_pk_add_f32 v[190:191], v[190:191], v[240:241]
	v_pk_add_f32 v[242:243], v[242:243], v[244:245]
	v_exp_f32_e32 v203, v159
	v_exp_f32_e32 v202, v163
	v_exp_f32_e32 v163, v160
	s_waitcnt lgkmcnt(8)
	v_mfma_f32_16x16x32_bf16 v[68:71], v[178:181], v[124:127], v[68:71]
	v_exp_f32_e32 v162, v164
	v_exp_f32_e32 v164, v170
	v_exp_f32_e32 v167, v167
	v_mfma_f32_16x16x32_bf16 v[80:83], v[178:181], v[128:131], v[80:83]
	v_pk_add_f32 v[246:247], v[246:247], v[248:249]
	v_pk_add_f32 v[250:251], v[250:251], v[252:253]
	v_exp_f32_e32 v170, v172
	v_exp_f32_e32 v169, v169
	v_cvt_pk_bf16_f32 v158, v201, v203
	s_waitcnt lgkmcnt(7)
	v_mfma_f32_16x16x32_bf16 v[60:63], v[182:185], v[124:127], v[60:63]
	v_mfma_f32_16x16x32_bf16 v[76:79], v[182:185], v[128:131], v[76:79]
	v_pk_add_f32 v[190:191], v[190:191], v[242:243]
	v_pk_add_f32 v[246:247], v[246:247], v[250:251]
	ds_read_b128 v[174:177], v132 offset:4096
	ds_read_b128 v[178:181], v132 offset:6144
	ds_read_b128 v[182:185], v132 offset:8192
	ds_read_b128 v[232:235], v132 offset:10240
	s_waitcnt lgkmcnt(10)
	v_mfma_f32_16x16x32_bf16 v[56:59], v[186:189], v[124:127], v[56:59]
	v_mfma_f32_16x16x32_bf16 v[64:67], v[186:189], v[128:131], v[64:67]
	v_pk_add_f32 v[190:191], v[190:191], v[246:247]
	v_pk_add_f32 v[110:111], v[110:111], v[190:191]
	ds_read_b128 v[186:189], v132 offset:12288
	ds_read_b128 v[236:239], v132 offset:14336
	s_waitcnt lgkmcnt(11)
	v_mfma_f32_16x16x32_bf16 v[36:39], v[216:219], v[124:127], v[36:39]
	v_mfma_f32_16x16x32_bf16 v[52:55], v[216:219], v[128:131], v[52:55]
	v_exp_f32_e32 v217, v161
	v_exp_f32_e32 v216, v165
	v_exp_f32_e32 v165, v166
	s_waitcnt lgkmcnt(10)
	v_mfma_f32_16x16x32_bf16 v[32:35], v[220:223], v[124:127], v[32:35]
	v_exp_f32_e32 v166, v171
	v_exp_f32_e32 v171, v168
	v_exp_f32_e32 v168, v173
	v_mfma_f32_16x16x32_bf16 v[48:51], v[220:223], v[128:131], v[48:51]
	v_cvt_pk_bf16_f32 v159, v163, v217
	v_cvt_pk_bf16_f32 v160, v165, v167
	v_cvt_pk_bf16_f32 v161, v171, v169
	s_waitcnt lgkmcnt(9)
	v_mfma_f32_16x16x32_bf16 v[28:31], v[224:227], v[124:127], v[28:31]
	v_mfma_f32_16x16x32_bf16 v[44:47], v[224:227], v[128:131], v[44:47]
	s_waitcnt lgkmcnt(8)
	v_mfma_f32_16x16x32_bf16 v[24:27], v[228:231], v[124:127], v[24:27]
	v_cvt_pk_bf16_f32 v124, v200, v202
	v_cvt_pk_bf16_f32 v125, v162, v216
	v_cvt_pk_bf16_f32 v126, v164, v166
	v_mfma_f32_16x16x32_bf16 v[40:43], v[228:231], v[128:131], v[40:43]
	v_cvt_pk_bf16_f32 v127, v170, v168
	s_waitcnt lgkmcnt(7)
	s_nop 1
	v_mfma_f32_16x16x32_bf16 v[84:87], v[150:153], v[124:127], v[84:87]
	v_pk_add_f32 v[200:201], v[200:201], v[202:203]
	v_pk_add_f32 v[162:163], v[162:163], v[216:217]
	s_waitcnt lgkmcnt(6)
	v_mfma_f32_16x16x32_bf16 v[80:83], v[154:157], v[124:127], v[80:83]
	v_pk_add_f32 v[164:165], v[164:165], v[166:167]
	v_pk_add_f32 v[170:171], v[170:171], v[168:169]
	v_lshl_add_u64 v[106:107], v[106:107], 0, s[66:67]
	v_lshl_add_u64 v[108:109], v[108:109], 0, s[76:77]
	s_waitcnt lgkmcnt(5)
	v_mfma_f32_16x16x32_bf16 v[76:79], v[174:177], v[124:127], v[76:79]
	v_pk_add_f32 v[200:201], v[200:201], v[162:163]
	v_pk_add_f32 v[164:165], v[164:165], v[170:171]
	s_waitcnt lgkmcnt(4)
	v_mfma_f32_16x16x32_bf16 v[64:67], v[178:181], v[124:127], v[64:67]
	v_pk_add_f32 v[200:201], v[200:201], v[164:165]
	v_pk_add_f32 v[110:111], v[110:111], v[200:201]
	s_waitcnt lgkmcnt(3)
	v_mfma_f32_16x16x32_bf16 v[52:55], v[182:185], v[124:127], v[52:55]
	s_waitcnt lgkmcnt(2)
	v_mfma_f32_16x16x32_bf16 v[48:51], v[232:235], v[124:127], v[48:51]
	s_waitcnt lgkmcnt(1)
	v_mfma_f32_16x16x32_bf16 v[44:47], v[186:189], v[124:127], v[44:47]
	s_waitcnt lgkmcnt(0)
	v_mfma_f32_16x16x32_bf16 v[40:43], v[236:239], v[124:127], v[40:43]
	v_add_u32_e32 v132, s17, v118
	ds_read_b128 v[240:243], v132
	ds_read_b128 v[128:131], v132 offset:64
	ds_read_b128 v[244:247], v132 offset:128
	ds_read_b128 v[248:251], v132 offset:192
	ds_read_b128 v[200:203], v132 offset:4352
	ds_read_b128 v[162:165], v132 offset:4416
	ds_read_b128 v[166:169], v132 offset:4480
	ds_read_b128 v[170:173], v132 offset:4544
	v_mfma_f32_16x16x32_bf16 v[72:75], v[150:153], v[158:161], v[72:75]
	v_mfma_f32_16x16x32_bf16 v[68:71], v[154:157], v[158:161], v[68:71]
	v_mfma_f32_16x16x32_bf16 v[60:63], v[174:177], v[158:161], v[60:63]
	v_add3_u32 v124, s18, v116, v117
	s_bitcmp1_b32 s5, 0
	s_cselect_b32 s4, s57, s70
	v_mfma_f32_16x16x32_bf16 v[56:59], v[178:181], v[158:161], v[56:59]
	s_waitcnt vmcnt(2)
	ds_write_b128 v124, v[92:95]
	ds_write_b128 v124, v[88:91] offset:16
	v_add_u32_e32 v88, s4, v122
	v_mfma_f32_16x16x32_bf16 v[36:39], v[182:185], v[158:161], v[36:39]
	s_waitcnt vmcnt(0)
	ds_write_b128 v88, v[100:103]
	v_add_u32_e32 v88, s4, v123
	v_mfma_f32_16x16x32_bf16 v[32:35], v[232:235], v[158:161], v[32:35]
	s_mov_b32 s19, s16
	s_mov_b32 s16, s17
	s_mov_b32 s17, s18
	s_mov_b32 s18, s19
	s_cmp_lg_u32 s23, s5
	s_mov_b32 s4, s5
	ds_write_b128 v88, v[96:99]
	v_mfma_f32_16x16x32_bf16 v[28:31], v[186:189], v[158:161], v[28:31]
	s_waitcnt lgkmcnt(0)
	s_barrier
	v_mfma_f32_16x16x32_bf16 v[24:27], v[236:239], v[158:161], v[24:27]
	s_cbranch_scc1 .LBB0_131
	v_add_u32_e32 v116, 0, v118
	ds_read_b128 v[88:91], v116 offset:17408
	ds_read_b128 v[92:95], v116 offset:17472
	ds_read_b128 v[96:99], v116 offset:17536
	ds_read_b128 v[100:103], v116 offset:17600
	ds_read_b128 v[106:109], v116 offset:21760
	ds_read_b128 v[122:125], v116 offset:21824
	ds_read_b128 v[126:129], v116 offset:21888
	ds_read_b128 v[150:153], v116 offset:21952
	ds_read_b128 v[154:157], v116 offset:26112
	ds_read_b128 v[158:161], v116 offset:26176
	ds_read_b128 v[162:165], v116 offset:26240
	ds_read_b128 v[166:169], v116 offset:26304
	ds_read_b128 v[170:173], v116 offset:30464
	ds_read_b128 v[174:177], v116 offset:30528
	ds_read_b128 v[178:181], v116 offset:30592
	ds_read_b128 v[182:185], v116 offset:30656
	s_waitcnt lgkmcnt(14)
	v_mfma_f32_16x16x32_bf16 v[88:91], v[88:91], v[12:15], v[16:19]
	v_mfma_f32_16x16x32_bf16 v[88:91], v[92:95], v[0:3], v[88:91]
	s_waitcnt lgkmcnt(13)
	v_mfma_f32_16x16x32_bf16 v[92:95], v[96:99], v[4:7], v[20:23]
	s_waitcnt lgkmcnt(11)
	v_mfma_f32_16x16x32_bf16 v[96:99], v[106:109], v[12:15], v[16:19]
	v_mfma_f32_16x16x32_bf16 v[92:95], v[100:103], v[8:11], v[92:95]
	s_waitcnt lgkmcnt(10)
	v_mfma_f32_16x16x32_bf16 v[96:99], v[122:125], v[0:3], v[96:99]
	s_waitcnt lgkmcnt(9)
	v_mfma_f32_16x16x32_bf16 v[100:103], v[126:129], v[4:7], v[20:23]
	s_waitcnt lgkmcnt(7)
	v_mfma_f32_16x16x32_bf16 v[106:109], v[154:157], v[12:15], v[16:19]
	s_waitcnt lgkmcnt(5)
	v_mfma_f32_16x16x32_bf16 v[122:125], v[162:165], v[4:7], v[20:23]
	s_waitcnt lgkmcnt(3)
	v_mfma_f32_16x16x32_bf16 v[12:15], v[170:173], v[12:15], v[16:19]
	s_waitcnt lgkmcnt(1)
	v_mfma_f32_16x16x32_bf16 v[4:7], v[178:181], v[4:7], v[20:23]
	v_mfma_f32_16x16x32_bf16 v[100:103], v[150:153], v[8:11], v[100:103]
	v_mfma_f32_16x16x32_bf16 v[106:109], v[158:161], v[0:3], v[106:109]
	v_mfma_f32_16x16x32_bf16 v[122:125], v[166:169], v[8:11], v[122:125]
	v_mfma_f32_16x16x32_bf16 v[0:3], v[174:177], v[0:3], v[12:15]
	s_waitcnt lgkmcnt(0)
	v_mfma_f32_16x16x32_bf16 v[4:7], v[182:185], v[8:11], v[4:7]
	v_add_u32_e32 v116, 0, v120
	v_add_u32_e32 v117, v116, v121
	v_add_u32_e32 v118, 0xc800, v117
	ds_read_b128 v[8:11], v117 offset:51200
	ds_read_b128 v[12:15], v117 offset:53248
	ds_read_b128 v[16:19], v117 offset:55296
	ds_read_b128 v[20:23], v117 offset:57344
	ds_read_b128 v[126:129], v117 offset:59392
	ds_read_b128 v[150:153], v117 offset:61440
	ds_read_b128 v[154:157], v117 offset:63488
	ds_read_b128 v[158:161], v118 offset:14336
	v_exp_f32_e32 v120, v88
	v_exp_f32_e32 v130, v92
	v_exp_f32_e32 v166, v89
	v_exp_f32_e32 v168, v93
	v_exp_f32_e32 v170, v90
	v_exp_f32_e32 v172, v94
	v_exp_f32_e32 v174, v91
	v_exp_f32_e32 v176, v95
	v_exp_f32_e32 v178, v96
	v_exp_f32_e32 v180, v100
	v_exp_f32_e32 v182, v97
	v_exp_f32_e32 v184, v101
	v_exp_f32_e32 v186, v98
	v_exp_f32_e32 v188, v102
	v_exp_f32_e32 v190, v99
	v_exp_f32_e32 v200, v103
	s_nop 0
	v_cvt_pk_bf16_f32 v88, v120, v166
	s_nop 0
	v_cvt_pk_bf16_f32 v89, v170, v174
	s_nop 0
	v_cvt_pk_bf16_f32 v90, v178, v182
	s_nop 0
	v_cvt_pk_bf16_f32 v91, v186, v190
	s_nop 0
	v_cvt_pk_bf16_f32 v92, v130, v168
	s_nop 0
	v_cvt_pk_bf16_f32 v93, v172, v176
	s_nop 0
	v_cvt_pk_bf16_f32 v94, v180, v184
	s_nop 0
	v_cvt_pk_bf16_f32 v95, v188, v200
	v_add_u32_e32 v121, v116, v119
	s_waitcnt lgkmcnt(7)
	v_mfma_f32_16x16x32_bf16 v[72:75], v[8:11], v[88:91], v[72:75]
	v_add_u32_e32 v131, 0xc800, v121
	v_exp_f32_e32 v167, v107
	v_exp_f32_e32 v169, v123
	v_mfma_f32_16x16x32_bf16 v[8:11], v[8:11], v[92:95], v[84:87]
	v_exp_f32_e32 v171, v108
	v_exp_f32_e32 v173, v124
	v_exp_f32_e32 v175, v109
	s_waitcnt lgkmcnt(6)
	v_mfma_f32_16x16x32_bf16 v[68:71], v[12:15], v[88:91], v[68:71]
	v_exp_f32_e32 v177, v125
	v_exp_f32_e32 v179, v0
	v_exp_f32_e32 v181, v4
	v_mfma_f32_16x16x32_bf16 v[12:15], v[12:15], v[92:95], v[80:83]
	v_exp_f32_e32 v183, v1
	v_exp_f32_e32 v185, v5
	v_exp_f32_e32 v187, v2
	s_waitcnt lgkmcnt(5)
	v_mfma_f32_16x16x32_bf16 v[60:63], v[16:19], v[88:91], v[60:63]
	v_exp_f32_e32 v189, v6
	v_exp_f32_e32 v191, v3
	v_exp_f32_e32 v201, v7
	v_mfma_f32_16x16x32_bf16 v[16:19], v[16:19], v[92:95], v[76:79]
	s_nop 2
	ds_read_b128 v[76:79], v121 offset:51200
	ds_read_b128 v[80:83], v121 offset:53248
	ds_read_b128 v[84:87], v121 offset:55296
	ds_read_b128 v[96:99], v121 offset:57344
	ds_read_b128 v[100:103], v121 offset:59392
	ds_read_b128 v[116:119], v121 offset:61440
	s_nop 0
	v_cvt_pk_bf16_f32 v1, v171, v175
	s_waitcnt lgkmcnt(10)
	v_mfma_f32_16x16x32_bf16 v[56:59], v[20:23], v[88:91], v[56:59]
	s_nop 0
	v_cvt_pk_bf16_f32 v2, v179, v183
	s_nop 0
	v_cvt_pk_bf16_f32 v3, v187, v191
	v_mfma_f32_16x16x32_bf16 v[20:23], v[20:23], v[92:95], v[64:67]
	s_nop 2
	ds_read_b128 v[64:67], v121 offset:63488
	ds_read_b128 v[162:165], v131 offset:14336
	v_exp_f32_e32 v121, v106
	v_exp_f32_e32 v131, v122
	s_waitcnt lgkmcnt(11)
	v_mfma_f32_16x16x32_bf16 v[36:39], v[126:129], v[88:91], v[36:39]
	s_nop 0
	v_cvt_pk_bf16_f32 v0, v121, v167
	v_mfma_f32_16x16x32_bf16 v[52:55], v[126:129], v[92:95], v[52:55]
	s_waitcnt lgkmcnt(10)
	v_mfma_f32_16x16x32_bf16 v[32:35], v[150:153], v[88:91], v[32:35]
	v_mfma_f32_16x16x32_bf16 v[48:51], v[150:153], v[92:95], v[48:51]
	s_waitcnt lgkmcnt(9)
	v_mfma_f32_16x16x32_bf16 v[28:31], v[154:157], v[88:91], v[28:31]
	v_mfma_f32_16x16x32_bf16 v[4:7], v[154:157], v[92:95], v[44:47]
	s_nop 0
	v_cvt_pk_bf16_f32 v44, v131, v169
	s_nop 0
	v_cvt_pk_bf16_f32 v45, v173, v177
	s_nop 0
	v_cvt_pk_bf16_f32 v46, v181, v185
	s_waitcnt lgkmcnt(8)
	v_mfma_f32_16x16x32_bf16 v[24:27], v[158:161], v[88:91], v[24:27]
	s_nop 0
	v_cvt_pk_bf16_f32 v47, v189, v201
	v_mfma_f32_16x16x32_bf16 v[40:43], v[158:161], v[92:95], v[40:43]
	s_waitcnt lgkmcnt(7)
	v_mfma_f32_16x16x32_bf16 v[72:75], v[76:79], v[0:3], v[72:75]
	s_waitcnt lgkmcnt(0)
	s_barrier
	v_mfma_f32_16x16x32_bf16 v[8:11], v[76:79], v[44:47], v[8:11]
	v_add_f32_e64 v76, v130, v168
	v_add_f32_e64 v77, v131, v169
	v_pk_add_f32 v[78:79], v[172:173], v[176:177]
	v_mfma_f32_16x16x32_bf16 v[68:71], v[80:83], v[0:3], v[68:71]
	v_add_f32_e64 v76, v76, v78
	v_add_f32_e64 v77, v77, v79
	v_pk_add_f32 v[78:79], v[180:181], v[184:185]
	v_mfma_f32_16x16x32_bf16 v[12:15], v[80:83], v[44:47], v[12:15]
	v_add_f32_e64 v80, v188, v200
	v_add_f32_e64 v81, v189, v201
	v_pk_add_f32 v[78:79], v[78:79], v[80:81]
	v_pk_add_f32 v[80:81], v[186:187], v[190:191]
	v_pk_add_f32 v[76:77], v[76:77], v[78:79]
	v_pk_add_f32 v[78:79], v[170:171], v[174:175]
	v_add_f32_e32 v76, v110, v76
	v_add_f32_e32 v82, v76, v77
	v_pk_add_f32 v[76:77], v[120:121], v[166:167]
	v_mfma_f32_16x16x32_bf16 v[28:31], v[64:67], v[0:3], v[28:31]
	v_add_f32_e64 v76, v76, v78
	v_add_f32_e64 v77, v77, v79
	v_pk_add_f32 v[78:79], v[178:179], v[182:183]
	v_mfma_f32_16x16x32_bf16 v[64:67], v[64:67], v[44:47], v[4:7]
	s_nop 2
	v_add_f32_e64 v4, v78, v80
	v_add_f32_e64 v5, v79, v81
	v_mfma_f32_16x16x32_bf16 v[60:63], v[84:87], v[0:3], v[60:63]
	v_add_f32_e64 v4, v76, v4
	v_add_f32_e64 v5, v77, v5
	v_add_f32_e32 v4, v111, v4
	v_mfma_f32_16x16x32_bf16 v[16:19], v[84:87], v[44:47], v[16:19]
	v_mfma_f32_16x16x32_bf16 v[56:59], v[96:99], v[0:3], v[56:59]
	v_mfma_f32_16x16x32_bf16 v[20:23], v[96:99], v[44:47], v[20:23]
	v_mfma_f32_16x16x32_bf16 v[36:39], v[100:103], v[0:3], v[36:39]
	v_mfma_f32_16x16x32_bf16 v[52:55], v[100:103], v[44:47], v[52:55]
	v_mfma_f32_16x16x32_bf16 v[32:35], v[116:119], v[0:3], v[32:35]
	v_mfma_f32_16x16x32_bf16 v[48:51], v[116:119], v[44:47], v[48:51]
	v_mfma_f32_16x16x32_bf16 v[24:27], v[162:165], v[0:3], v[24:27]
	v_add_f32_e32 v0, v4, v5
	v_mfma_f32_16x16x32_bf16 v[40:43], v[162:165], v[44:47], v[40:43]
	s_setprio 0
	ds_bpermute_b32 v1, v114, v0
	ds_bpermute_b32 v2, v114, v82
	s_waitcnt lgkmcnt(1)
	v_add_f32_e32 v0, v0, v1
	s_waitcnt lgkmcnt(0)
	v_add_f32_e32 v1, v82, v2
	ds_bpermute_b32 v2, v115, v0
	ds_bpermute_b32 v3, v115, v1
	s_waitcnt lgkmcnt(1)
	v_add_f32_e32 v0, v0, v2
	v_div_scale_f32 v2, s[4:5], v0, v0, 1.0
	v_rcp_f32_e32 v4, v2
	s_waitcnt lgkmcnt(0)
	v_add_f32_e32 v1, v1, v3
	v_div_scale_f32 v3, vcc, 1.0, v0, 1.0
	v_fma_f32 v7, -v2, v4, 1.0
	v_fmac_f32_e32 v4, v7, v4
	v_div_scale_f32 v5, s[4:5], v1, v1, v113
	v_mul_f32_e32 v7, v3, v4
	v_rcp_f32_e32 v6, v5
	v_fma_f32 v44, -v2, v7, v3
	v_fmac_f32_e32 v7, v44, v4
	v_fma_f32 v2, -v2, v7, v3
	v_div_fmas_f32 v2, v2, v4, v7
	v_div_fixup_f32 v44, v2, v0, 1.0
	v_fma_f32 v0, -v5, v6, 1.0
	v_fmac_f32_e32 v6, v0, v6
	v_div_scale_f32 v0, vcc, v113, v1, v113
	v_mul_f32_e32 v2, v0, v6
	v_fma_f32 v3, -v5, v2, v0
	v_fmac_f32_e32 v2, v3, v6
	v_fma_f32 v0, -v5, v2, v0
	v_div_fmas_f32 v0, v0, v6, v2
	s_mov_b64 s[4:5], s[0:1]
	v_div_fixup_f32 v46, v0, v1, v113
	v_pk_mul_f32 v[0:1], v[8:9], v[46:47] op_sel_hi:[1,0]
	v_pk_mul_f32 v[2:3], v[10:11], v[46:47] op_sel_hi:[1,0]
	s_load_dwordx2 s[4:5], s[4:5], 0x78
	v_pk_fma_f32 v[74:75], v[74:75], v[44:45], v[2:3] op_sel_hi:[1,0,1] neg_lo:[0,0,1] neg_hi:[0,0,1]
	v_pk_fma_f32 v[72:73], v[72:73], v[44:45], v[0:1] op_sel_hi:[1,0,1] neg_lo:[0,0,1] neg_hi:[0,0,1]
	v_pk_mul_f32 v[0:1], v[12:13], v[46:47] op_sel_hi:[1,0]
	v_pk_mul_f32 v[2:3], v[14:15], v[46:47] op_sel_hi:[1,0]
	v_pk_fma_f32 v[68:69], v[68:69], v[44:45], v[0:1] op_sel_hi:[1,0,1] neg_lo:[0,0,1] neg_hi:[0,0,1]
	v_pk_fma_f32 v[70:71], v[70:71], v[44:45], v[2:3] op_sel_hi:[1,0,1] neg_lo:[0,0,1] neg_hi:[0,0,1]
	v_pk_mul_f32 v[0:1], v[16:17], v[46:47] op_sel_hi:[1,0]
	v_pk_mul_f32 v[2:3], v[18:19], v[46:47] op_sel_hi:[1,0]
	v_pk_fma_f32 v[60:61], v[60:61], v[44:45], v[0:1] op_sel_hi:[1,0,1] neg_lo:[0,0,1] neg_hi:[0,0,1]
	v_pk_fma_f32 v[16:17], v[62:63], v[44:45], v[2:3] op_sel_hi:[1,0,1] neg_lo:[0,0,1] neg_hi:[0,0,1]
	v_pk_mul_f32 v[0:1], v[20:21], v[46:47] op_sel_hi:[1,0]
	v_pk_mul_f32 v[2:3], v[22:23], v[46:47] op_sel_hi:[1,0]
	v_pk_fma_f32 v[14:15], v[56:57], v[44:45], v[0:1] op_sel_hi:[1,0,1] neg_lo:[0,0,1] neg_hi:[0,0,1]
	v_pk_fma_f32 v[12:13], v[58:59], v[44:45], v[2:3] op_sel_hi:[1,0,1] neg_lo:[0,0,1] neg_hi:[0,0,1]
	v_pk_mul_f32 v[0:1], v[52:53], v[46:47] op_sel_hi:[1,0]
	v_pk_mul_f32 v[2:3], v[54:55], v[46:47] op_sel_hi:[1,0]
	v_pk_fma_f32 v[10:11], v[36:37], v[44:45], v[0:1] op_sel_hi:[1,0,1] neg_lo:[0,0,1] neg_hi:[0,0,1]
	v_pk_fma_f32 v[8:9], v[38:39], v[44:45], v[2:3] op_sel_hi:[1,0,1] neg_lo:[0,0,1] neg_hi:[0,0,1]
	v_pk_mul_f32 v[0:1], v[48:49], v[46:47] op_sel_hi:[1,0]
	v_pk_mul_f32 v[2:3], v[50:51], v[46:47] op_sel_hi:[1,0]
	s_waitcnt lgkmcnt(0)
	s_add_u32 s4, s4, s8
	v_pk_fma_f32 v[4:5], v[34:35], v[44:45], v[2:3] op_sel_hi:[1,0,1] neg_lo:[0,0,1] neg_hi:[0,0,1]
	v_pk_fma_f32 v[6:7], v[32:33], v[44:45], v[0:1] op_sel_hi:[1,0,1] neg_lo:[0,0,1] neg_hi:[0,0,1]
	v_pk_mul_f32 v[2:3], v[64:65], v[46:47] op_sel_hi:[1,0]
	v_pk_mul_f32 v[0:1], v[66:67], v[46:47] op_sel_hi:[1,0]
	v_pk_mul_f32 v[18:19], v[40:41], v[46:47] op_sel_hi:[1,0]
	v_pk_mul_f32 v[20:21], v[42:43], v[46:47] op_sel_hi:[1,0]
	s_addc_u32 s5, s5, s9
	v_lshlrev_b32_e32 v46, 4, v105
	v_pk_fma_f32 v[0:1], v[30:31], v[44:45], v[0:1] op_sel_hi:[1,0,1] neg_lo:[0,0,1] neg_hi:[0,0,1]
	v_pk_fma_f32 v[2:3], v[28:29], v[44:45], v[2:3] op_sel_hi:[1,0,1] neg_lo:[0,0,1] neg_hi:[0,0,1]
	v_pk_fma_f32 v[50:51], v[26:27], v[44:45], v[20:21] op_sel_hi:[1,0,1] neg_lo:[0,0,1] neg_hi:[0,0,1]
	v_pk_fma_f32 v[52:53], v[24:25], v[44:45], v[18:19] op_sel_hi:[1,0,1] neg_lo:[0,0,1] neg_hi:[0,0,1]
	global_load_dwordx4 v[18:21], v46, s[4:5]
	global_load_dwordx4 v[22:25], v46, s[4:5] offset:64
	global_load_dwordx4 v[26:29], v46, s[4:5] offset:128
	global_load_dwordx4 v[30:33], v46, s[4:5] offset:192
	global_load_dwordx4 v[34:37], v46, s[4:5] offset:256
	global_load_dwordx4 v[38:41], v46, s[4:5] offset:320
	global_load_dwordx4 v[42:45], v46, s[4:5] offset:384
	s_nop 0
	global_load_dwordx4 v[46:49], v46, s[4:5] offset:448
	v_mov_b32_e32 v56, v73
	v_mov_b32_e32 v57, v69
	v_mov_b32_e32 v54, v72
	v_mov_b32_e32 v55, v68
	v_pk_mul_f32 v[56:57], v[56:57], v[56:57]
	v_mov_b32_e32 v58, v15
	v_pk_fma_f32 v[54:55], v[54:55], v[54:55], v[56:57]
	v_mov_b32_e32 v56, v74
	v_mov_b32_e32 v57, v70
	v_pk_fma_f32 v[54:55], v[56:57], v[56:57], v[54:55]
	v_mov_b32_e32 v56, v75
	v_mov_b32_e32 v57, v71
	v_mov_b32_e32 v59, v61
	v_pk_fma_f32 v[54:55], v[56:57], v[56:57], v[54:55]
	v_mov_b32_e32 v56, v14
	v_mov_b32_e32 v57, v60
	v_pk_mul_f32 v[58:59], v[58:59], v[58:59]
	v_mov_b32_e32 v62, v7
	v_pk_fma_f32 v[56:57], v[56:57], v[56:57], v[58:59]
	v_mov_b32_e32 v58, v12
	v_mov_b32_e32 v59, v16
	v_pk_fma_f32 v[56:57], v[58:59], v[58:59], v[56:57]
	v_mov_b32_e32 v58, v13
	v_mov_b32_e32 v59, v17
	v_mov_b32_e32 v63, v11
	v_pk_fma_f32 v[56:57], v[58:59], v[58:59], v[56:57]
	v_mov_b32_e32 v58, v6
	v_mov_b32_e32 v59, v10
	v_pk_mul_f32 v[62:63], v[62:63], v[62:63]
	v_mov_b32_e32 v64, v53
	v_pk_fma_f32 v[58:59], v[58:59], v[58:59], v[62:63]
	v_mov_b32_e32 v62, v4
	v_mov_b32_e32 v63, v8
	v_pk_fma_f32 v[58:59], v[62:63], v[62:63], v[58:59]
	v_mov_b32_e32 v62, v5
	v_mov_b32_e32 v63, v9
	v_mov_b32_e32 v65, v3
	v_add_f32_e32 v54, v54, v55
	v_pk_fma_f32 v[58:59], v[62:63], v[62:63], v[58:59]
	v_mov_b32_e32 v62, v52
	v_mov_b32_e32 v63, v2
	v_pk_mul_f32 v[64:65], v[64:65], v[64:65]
	v_add_f32_e32 v54, v57, v54
	v_pk_fma_f32 v[62:63], v[62:63], v[62:63], v[64:65]
	v_mov_b32_e32 v64, v50
	v_mov_b32_e32 v65, v0
	v_add_f32_e32 v54, v56, v54
	v_pk_fma_f32 v[62:63], v[64:65], v[64:65], v[62:63]
	v_mov_b32_e32 v64, v51
	v_mov_b32_e32 v65, v1
	v_add_f32_e32 v54, v59, v54
	v_pk_fma_f32 v[62:63], v[64:65], v[64:65], v[62:63]
	v_add_f32_e32 v54, v58, v54
	v_add_f32_e32 v54, v63, v54
	v_add_f32_e32 v54, v62, v54
	ds_bpermute_b32 v55, v114, v54
	v_sub_f32_e32 v56, 1.0, v112
	s_waitcnt lgkmcnt(0)
	v_add_f32_e32 v54, v54, v55
	ds_bpermute_b32 v55, v115, v54
	s_waitcnt lgkmcnt(0)
	v_add_f32_e32 v54, v54, v55
	v_fmamk_f32 v54, v54, 0x3c000000, v137
	v_mul_f32_e32 v55, 0x4b800000, v54
	v_cmp_gt_f32_e32 vcc, s94, v54
	s_nop 1
	v_cndmask_b32_e32 v54, v54, v55, vcc
	v_rsq_f32_e32 v54, v54
	s_nop 0
	v_mul_f32_e32 v55, 0x45800000, v54
	v_cndmask_b32_e32 v54, v54, v55, vcc
	v_mul_f32_e32 v54, v56, v54
	v_mov_b64_e32 v[56:57], s[12:13]
	v_mad_i64_i32 v[56:57], s[4:5], v104, s96, v[56:57]
	s_lshl_b32 s58, s22, 1
	v_pk_mul_f32 v[58:59], v[72:73], v[54:55] op_sel_hi:[1,0]
	v_lshl_add_u64 v[56:57], v[56:57], 0, s[58:59]
	v_lshlrev_b32_e32 v132, 3, v105
	v_pk_mul_f32 v[62:63], v[74:75], v[54:55] op_sel_hi:[1,0]
	s_waitcnt vmcnt(7)
	v_pk_mul_f32 v[18:19], v[18:19], v[58:59]
	v_lshl_add_u64 v[56:57], v[56:57], 0, v[132:133]
	v_pk_mul_f32 v[20:21], v[20:21], v[62:63]
	v_cvt_pk_bf16_f32 v18, v18, v19
	v_pk_mul_f32 v[2:3], v[2:3], v[54:55] op_sel_hi:[1,0]
	v_cvt_pk_bf16_f32 v19, v20, v21
	global_store_dwordx2 v[56:57], v[18:19], off
	v_pk_mul_f32 v[18:19], v[68:69], v[54:55] op_sel_hi:[1,0]
	v_pk_mul_f32 v[20:21], v[70:71], v[54:55] op_sel_hi:[1,0]
	s_waitcnt vmcnt(7)
	v_pk_mul_f32 v[18:19], v[22:23], v[18:19]
	v_pk_mul_f32 v[0:1], v[0:1], v[54:55] op_sel_hi:[1,0]
	v_pk_mul_f32 v[20:21], v[24:25], v[20:21]
	v_cvt_pk_bf16_f32 v18, v18, v19
	s_waitcnt vmcnt(2)
	v_pk_mul_f32 v[0:1], v[44:45], v[0:1]
	v_cvt_pk_bf16_f32 v19, v20, v21
	v_pk_mul_f32 v[2:3], v[42:43], v[2:3]
	global_store_dwordx2 v[56:57], v[18:19], off offset:32
	v_pk_mul_f32 v[18:19], v[60:61], v[54:55] op_sel_hi:[1,0]
	v_pk_mul_f32 v[14:15], v[14:15], v[54:55] op_sel_hi:[1,0]
	v_pk_mul_f32 v[10:11], v[10:11], v[54:55] op_sel_hi:[1,0]
	v_pk_mul_f32 v[6:7], v[6:7], v[54:55] op_sel_hi:[1,0]
	v_cvt_pk_bf16_f32 v2, v2, v3
	v_cvt_pk_bf16_f32 v3, v0, v1
	v_pk_mul_f32 v[0:1], v[52:53], v[54:55] op_sel_hi:[1,0]
	v_pk_mul_f32 v[16:17], v[16:17], v[54:55] op_sel_hi:[1,0]
	v_pk_mul_f32 v[18:19], v[26:27], v[18:19]
	v_pk_mul_f32 v[12:13], v[12:13], v[54:55] op_sel_hi:[1,0]
	v_pk_mul_f32 v[14:15], v[30:31], v[14:15]
	v_pk_mul_f32 v[8:9], v[8:9], v[54:55] op_sel_hi:[1,0]
	v_pk_mul_f32 v[10:11], v[34:35], v[10:11]
	v_pk_mul_f32 v[4:5], v[4:5], v[54:55] op_sel_hi:[1,0]
	v_pk_mul_f32 v[6:7], v[38:39], v[6:7]
	global_store_dwordx2 v[56:57], v[2:3], off offset:192
	v_pk_mul_f32 v[2:3], v[50:51], v[54:55] op_sel_hi:[1,0]
	s_waitcnt vmcnt(3)
	v_pk_mul_f32 v[0:1], v[46:47], v[0:1]
	s_mov_b64 s[4:5], 0
	v_pk_mul_f32 v[16:17], v[28:29], v[16:17]
	v_cvt_pk_bf16_f32 v18, v18, v19
	v_pk_mul_f32 v[12:13], v[32:33], v[12:13]
	v_cvt_pk_bf16_f32 v19, v16, v17
	global_store_dwordx2 v[56:57], v[18:19], off offset:64
	v_cvt_pk_bf16_f32 v14, v14, v15
	v_cvt_pk_bf16_f32 v15, v12, v13
	global_store_dwordx2 v[56:57], v[14:15], off offset:96
	v_pk_mul_f32 v[8:9], v[36:37], v[8:9]
	v_cvt_pk_bf16_f32 v10, v10, v11
	v_pk_mul_f32 v[4:5], v[40:41], v[4:5]
	v_cvt_pk_bf16_f32 v11, v8, v9
	global_store_dwordx2 v[56:57], v[10:11], off offset:128
	v_cvt_pk_bf16_f32 v6, v6, v7
	v_cvt_pk_bf16_f32 v7, v4, v5
	global_store_dwordx2 v[56:57], v[6:7], off offset:160
	v_pk_mul_f32 v[2:3], v[48:49], v[2:3]
	v_cvt_pk_bf16_f32 v0, v0, v1
	s_nop 0
	v_cvt_pk_bf16_f32 v1, v2, v3
	global_store_dwordx2 v[56:57], v[0:1], off offset:224
	s_branch .LBB0_77
	s_nop 0
	s_nop 0
	s_nop 0
	s_nop 0
	s_nop 0
	s_nop 0
	s_nop 0
	s_nop 0
	s_nop 0
	s_nop 0
	s_nop 0
	s_nop 0
	s_nop 0
	s_nop 0
	s_nop 0
	s_nop 0
	s_nop 0
	s_nop 0
	s_nop 0
	s_nop 0
	s_nop 0
	s_nop 0
	s_nop 0
	s_nop 0
	s_nop 0
	s_nop 0
	s_nop 0
	s_nop 0
	s_nop 0
	s_nop 0
	s_nop 0
	s_nop 0
	s_nop 0
	s_nop 0
	s_nop 0
	s_nop 0
	s_nop 0
	s_nop 0
	s_nop 0
	s_nop 0
	s_nop 0
	s_nop 0
	s_nop 0
	s_nop 0
